# neighbourhood attention: MFMA under softmax VALU, waves 4-7 delayed, next unit prefetched under the epilogue, 16-byte gate loads and output stores via permlane16_swap
# baseline (speedup 1.0000x reference)
.LBB0_227:
	s_or_b64 exec, exec, s[6:7]
	s_lshr_b32 s10, s22, 1
	s_mov_b64 s[6:7], -1
	s_and_b64 vcc, exec, s[4:5]
	s_waitcnt lgkmcnt(0)
	s_barrier
	s_cbranch_vccz .LBB0_331
	s_movk_i32 s41, 0x480
	s_cmp_eq_u32 s22, 3
	s_cselect_b32 s41, 0x400, s41
	s_mov_b32 s53, 0x3e0293ee
	v_readlane_b32 s24, v253, 8
	v_readlane_b32 s25, v253, 9
	s_mul_i32 s1, s10, 0xe880
	s_add_u32 s24, s24, s1
	s_addc_u32 s25, s25, 0
	s_add_u32 s26, s92, 0x18e00000
	s_addc_u32 s27, s93, 0
	s_add_u32 s28, s92, 0x2ae00000
	s_addc_u32 s29, s93, 0
	v_readfirstlane_b32 s36, v172
	s_lshr_b32 s36, s36, 6
	s_and_b32 s37, s36, 3
	s_lshr_b32 s38, s36, 2
	s_lshl_b32 s39, s37, 3
	s_cmp_gt_u32 s37, 1
	s_cselect_b32 s1, 8, 0
	s_add_u32 s39, s39, s1
	v_and_b32_e32 v192, 15, v246
	v_lshrrev_b32_e32 v193, 4, v246
	v_lshrrev_b32_e32 v224, 4, v172
	v_and_b32_e32 v225, 15, v172
	v_lshlrev_b32_e32 v194, 15, v224
	v_lshl_add_u32 v194, v225, 4, v194
	v_add_u32_e32 v195, 0x100000, v194
	v_mul_u32_u24_e32 v196, 0x110, v224
	v_lshl_add_u32 v196, v225, 4, v196
	v_mul_u32_u24_e32 v197, 0x120, v224
	v_lshl_add_u32 v197, v225, 4, v197
	v_add_u32_e32 v197, 0x4400, v197
	v_mul_u32_u24_e32 v199, 0x110, v192
	v_lshl_add_u32 v199, v193, 4, v199
	s_mul_i32 s1, s39, 0x110
	v_add_u32_e32 v198, s1, v199
	v_lshrrev_b32_e32 v224, 2, v192
	v_lshl_add_u32 v224, v193, 2, v224
	v_mul_u32_u24_e32 v201, 0x120, v224
	v_and_b32_e32 v225, 3, v192
	v_lshl_add_u32 v201, v225, 3, v201
	v_add_u32_e32 v201, 0x4400, v201
	s_mul_i32 s1, s39, 0x120
	v_add_u32_e32 v200, s1, v201
	v_lshl_add_u32 v228, s37, 4, v192
	v_add_u32_e32 v224, -8, v228
	v_max_i32_e32 v224, 0, v224
	v_min_i32_e32 v229, 48, v224
	v_lshl_add_u32 v230, v193, 2, s39
	v_add_u32_e32 v224, 0, v230
	v_sub_u32_e32 v225, v224, v229
	v_cmp_gt_u32_e32 vcc, 16, v225
	v_sub_u32_e32 v224, v224, v228
	v_add_u32_e32 v224, 15, v224
	v_cndmask_b32_e32 v224, 31, v224, vcc
	v_lshlrev_b32_e32 v202, 2, v224
	v_add_u32_e32 v224, 1, v230
	v_sub_u32_e32 v225, v224, v229
	v_cmp_gt_u32_e32 vcc, 16, v225
	v_sub_u32_e32 v224, v224, v228
	v_add_u32_e32 v224, 15, v224
	v_cndmask_b32_e32 v224, 31, v224, vcc
	v_lshlrev_b32_e32 v203, 2, v224
	v_add_u32_e32 v224, 2, v230
	v_sub_u32_e32 v225, v224, v229
	v_cmp_gt_u32_e32 vcc, 16, v225
	v_sub_u32_e32 v224, v224, v228
	v_add_u32_e32 v224, 15, v224
	v_cndmask_b32_e32 v224, 31, v224, vcc
	v_lshlrev_b32_e32 v204, 2, v224
	v_add_u32_e32 v224, 3, v230
	v_sub_u32_e32 v225, v224, v229
	v_cmp_gt_u32_e32 vcc, 16, v225
	v_sub_u32_e32 v224, v224, v228
	v_add_u32_e32 v224, 15, v224
	v_cndmask_b32_e32 v224, 31, v224, vcc
	v_lshlrev_b32_e32 v205, 2, v224
	v_add_u32_e32 v224, 16, v230
	v_sub_u32_e32 v225, v224, v229
	v_cmp_gt_u32_e32 vcc, 16, v225
	v_sub_u32_e32 v224, v224, v228
	v_add_u32_e32 v224, 15, v224
	v_cndmask_b32_e32 v224, 31, v224, vcc
	v_lshlrev_b32_e32 v206, 2, v224
	v_add_u32_e32 v224, 17, v230
	v_sub_u32_e32 v225, v224, v229
	v_cmp_gt_u32_e32 vcc, 16, v225
	v_sub_u32_e32 v224, v224, v228
	v_add_u32_e32 v224, 15, v224
	v_cndmask_b32_e32 v224, 31, v224, vcc
	v_lshlrev_b32_e32 v207, 2, v224
	v_add_u32_e32 v224, 18, v230
	v_sub_u32_e32 v225, v224, v229
	v_cmp_gt_u32_e32 vcc, 16, v225
	v_sub_u32_e32 v224, v224, v228
	v_add_u32_e32 v224, 15, v224
	v_cndmask_b32_e32 v224, 31, v224, vcc
	v_lshlrev_b32_e32 v208, 2, v224
	v_add_u32_e32 v224, 19, v230
	v_sub_u32_e32 v225, v224, v229
	v_cmp_gt_u32_e32 vcc, 16, v225
	v_sub_u32_e32 v224, v224, v228
	v_add_u32_e32 v224, 15, v224
	v_cndmask_b32_e32 v224, 31, v224, vcc
	v_lshlrev_b32_e32 v209, 2, v224
	v_lshlrev_b32_e32 v210, 15, v192
	v_lshl_add_u32 v210, v193, 4, v210
	v_lshlrev_b32_e32 v211, 15, v192
	v_lshl_add_u32 v211, v193, 3, v211
	v_and_b32_e32 v224, 1, v193
	v_mul_u32_u24_e32 v224, 24, v224
	v_add_u32_e32 v211, v211, v224
	v_lshlrev_b32_e32 v212, 13, v192
	v_lshl_add_u32 v212, v193, 3, v212
	v_add_u32_e32 v212, v212, v224
	v_lshrrev_b32_e32 v224, 5, v172
	v_and_b32_e32 v225, 31, v172
	v_cmp_gt_u32_e32 vcc, 15, v224
	v_cmp_gt_u32_e64 s[22:23], 31, v225
	s_and_b64 s[22:23], s[22:23], vcc
	v_mul_u32_u24_e32 v224, 31, v224
	v_add_lshl_u32 v224, v224, v225, 2
	v_cndmask_b32_e64 v213, 0, v224, s[22:23]
	v_lshlrev_b32_e32 v214, 2, v172
	v_add_u32_e32 v214, 0x11800, v214
	v_xor_b32_e32 v215, 16, v246
	v_lshlrev_b32_e32 v215, 2, v215
	v_xor_b32_e32 v216, 32, v246
	v_lshlrev_b32_e32 v216, 2, v216
	v_xor_b32_e32 v217, 48, v246
	v_lshlrev_b32_e32 v217, 2, v217
	s_mov_b32 s40, s62
	s_cmp_ge_u32 s40, 0x400
	s_cbranch_scc1 .Lna_dec_ctx_0
	s_mov_b32 s45, 0
	s_cmp_eq_u32 s94, 0x100
	s_cbranch_scc0 .Lna_dec_gen_0
	s_lshr_b32 s1, s40, 8
	s_and_b32 s2, s40, 0xff
	s_lshl_b32 s1, s1, 5
	s_and_b32 s4, s2, 7
	s_lshl_b32 s4, s4, 2
	s_add_u32 s1, s1, s4
	s_lshr_b32 s4, s2, 6
	s_add_u32 s1, s1, s4
	s_bfe_u32 s44, s2, 0x30003
	s_branch .Lna_dec_l2_0

.Lna_tb_done0:
	s_lshl_b32 s1, s1, 15
	s_lshl_b32 s2, s43, 8
	s_add_u32 s1, s1, s2
	s_add_u32 s1, s1, 0x2000
	s_add_u32 s54, s26, s1
	s_addc_u32 s55, s27, 0
	s_add_u32 s56, s54, 0x2000
	s_addc_u32 s57, s55, 0
	global_load_dwordx4 v[96:99], v194, s[54:55]
	global_load_dwordx4 v[100:103], v194, s[56:57]
	global_load_dwordx4 v[104:107], v195, s[54:55]
	global_load_dwordx4 v[108:111], v195, s[56:57]
	v_mov_b64_e32 v[0:1], 0
	v_mov_b64_e32 v[2:3], 0
	v_mov_b64_e32 v[4:5], 0
	v_mov_b64_e32 v[6:7], 0
	v_mov_b64_e32 v[8:9], 0
	v_mov_b64_e32 v[10:11], 0
	v_mov_b64_e32 v[12:13], 0
	v_mov_b64_e32 v[14:15], 0
	v_mov_b64_e32 v[16:17], 0
	v_mov_b64_e32 v[18:19], 0
	v_mov_b64_e32 v[20:21], 0
	v_mov_b64_e32 v[22:23], 0
	v_mov_b64_e32 v[24:25], 0
	v_mov_b64_e32 v[26:27], 0
	v_mov_b64_e32 v[28:29], 0
	v_mov_b64_e32 v[30:31], 0
	v_mov_b64_e32 v[32:33], 0
	v_mov_b64_e32 v[34:35], 0
	v_mov_b64_e32 v[36:37], 0
	v_mov_b64_e32 v[38:39], 0
	v_mov_b64_e32 v[40:41], 0
	v_mov_b64_e32 v[42:43], 0
	v_mov_b64_e32 v[44:45], 0
	v_mov_b64_e32 v[46:47], 0
	v_mov_b64_e32 v[48:49], 0
	v_mov_b64_e32 v[50:51], 0
	v_mov_b64_e32 v[52:53], 0
	v_mov_b64_e32 v[54:55], 0
	v_mov_b64_e32 v[56:57], 0
	v_mov_b64_e32 v[58:59], 0
	v_mov_b64_e32 v[60:61], 0
	v_mov_b64_e32 v[62:63], 0
	v_mov_b32_e32 v218, 0xf149f2ca
	v_mov_b32_e32 v221, 0xf149f2ca
	v_mov_b32_e32 v219, 0xf149f2ca
	v_mov_b32_e32 v222, 0xf149f2ca
	v_mov_b32_e32 v220, 0
	v_mov_b32_e32 v223, 0
	s_waitcnt vmcnt(4)
	v_mul_f32_e32 v236, 0x3fb8aa3b, v236
	v_cndmask_b32_e64 v236, v247, v236, s[22:23]
	ds_write_b32 v214, v236
	s_waitcnt vmcnt(0)
	v_mov_b32_e32 v234, v196
	v_mov_b32_e32 v235, v197
	ds_write_b128 v234, v[96:99]
	ds_write_b128 v235, v[100:103]
	ds_write_b128 v234, v[104:107] offset:8704
	ds_write_b128 v235, v[108:111] offset:9216
	s_waitcnt lgkmcnt(0)
	s_barrier
	s_branch .Lna_itloop
.Lna_unit_next:
	v_mov_b64_e32 v[0:1], 0
	v_mov_b64_e32 v[2:3], 0
	v_mov_b64_e32 v[4:5], 0
	v_mov_b64_e32 v[6:7], 0
	v_mov_b64_e32 v[8:9], 0
	v_mov_b64_e32 v[10:11], 0
	v_mov_b64_e32 v[12:13], 0
	v_mov_b64_e32 v[14:15], 0
	v_mov_b64_e32 v[16:17], 0
	v_mov_b64_e32 v[18:19], 0
	v_mov_b64_e32 v[20:21], 0
	v_mov_b64_e32 v[22:23], 0
	v_mov_b64_e32 v[24:25], 0
	v_mov_b64_e32 v[26:27], 0
	v_mov_b64_e32 v[28:29], 0
	v_mov_b64_e32 v[30:31], 0
	v_mov_b64_e32 v[32:33], 0
	v_mov_b64_e32 v[34:35], 0
	v_mov_b64_e32 v[36:37], 0
	v_mov_b64_e32 v[38:39], 0
	v_mov_b64_e32 v[40:41], 0
	v_mov_b64_e32 v[42:43], 0
	v_mov_b64_e32 v[44:45], 0
	v_mov_b64_e32 v[46:47], 0
	v_mov_b64_e32 v[48:49], 0
	v_mov_b64_e32 v[50:51], 0
	v_mov_b64_e32 v[52:53], 0
	v_mov_b64_e32 v[54:55], 0
	v_mov_b64_e32 v[56:57], 0
	v_mov_b64_e32 v[58:59], 0
	v_mov_b64_e32 v[60:61], 0
	v_mov_b64_e32 v[62:63], 0
	v_mov_b32_e32 v218, 0xf149f2ca
	v_mov_b32_e32 v221, 0xf149f2ca
	v_mov_b32_e32 v219, 0xf149f2ca
	v_mov_b32_e32 v222, 0xf149f2ca
	v_mov_b32_e32 v220, 0
	v_mov_b32_e32 v223, 0
	s_waitcnt vmcnt(12)
	v_mul_f32_e32 v236, 0x3fb8aa3b, v236
	v_cndmask_b32_e64 v236, v247, v236, s[22:23]
	ds_write_b32 v214, v236
	s_waitcnt vmcnt(8)
	v_mov_b32_e32 v234, v196
	v_mov_b32_e32 v235, v197
	ds_write_b128 v234, v[96:99]
	ds_write_b128 v235, v[100:103]
	ds_write_b128 v234, v[104:107] offset:8704
	ds_write_b128 v235, v[108:111] offset:9216
	s_waitcnt lgkmcnt(0)
	s_barrier

.Lna_it:
	s_cmp_lt_u32 s36, 4
	s_cbranch_scc1 .Lna_nostag
	s_sleep 5
.Lna_nostag:
	s_add_u32 s11, s52, 1
	s_cmp_lt_u32 s11, s51
	s_cselect_b32 s67, 1, 0
	s_cbranch_scc0 .Lna_noload
	s_cmp_lt_u32 s11, s50
	s_cbranch_scc0 .Lna_tb_ctx1
	s_add_u32 s1, s49, s11
	s_lshl_b32 s1, s1, 6
	s_lshl_b32 s2, s42, 11
	s_add_u32 s1, s1, s2
	s_branch .Lna_tb_done1
.Lna_tb_ctx1:
	s_sub_u32 s1, s11, s50
	s_lshl_b32 s1, s1, 6
	s_lshl_b32 s2, s42, 8
	s_add_u32 s1, s1, s2
	s_add_u32 s1, s1, 0x2000
.Lna_tb_done1:
	s_lshl_b32 s1, s1, 15
	s_lshl_b32 s2, s43, 8
	s_add_u32 s1, s1, s2
	s_add_u32 s1, s1, 0x2000
	s_add_u32 s54, s26, s1
	s_addc_u32 s55, s27, 0
	s_add_u32 s56, s54, 0x2000
	s_addc_u32 s57, s55, 0
	global_load_dwordx4 v[96:99], v194, s[54:55]
	global_load_dwordx4 v[100:103], v194, s[56:57]
	global_load_dwordx4 v[104:107], v195, s[54:55]
	global_load_dwordx4 v[108:111], v195, s[56:57]
.Lna_noload:
	s_cmp_lt_u32 s52, s50
	s_cbranch_scc0 .Lna_ctx
	s_add_u32 s1, s49, s52
	s_sub_u32 s2, s1, s47
	s_cmp_lt_u32 s2, 8
	s_cselect_b32 s4, 1, 0
	s_sub_u32 s2, s1, s48
	s_cmp_lt_u32 s2, 8
	s_cselect_b32 s5, 1, 0
	s_or_b32 s6, s4, s5
	s_cmp_eq_u32 s6, 0
	s_cbranch_scc1 .Lna_endcompute
	s_sub_u32 s2, s1, s46
	s_add_u32 s2, s2, 7
	s_cmp_eq_u32 s4, 1
	s_cselect_b32 s6, s2, 15
	s_lshl_b32 s6, s6, 7
	s_add_u32 s78, s6, 0x11800
	s_sub_u32 s2, s2, 1
	s_cmp_eq_u32 s5, 1
	s_cselect_b32 s6, s2, 15
	s_lshl_b32 s6, s6, 7
	s_add_u32 s79, s6, 0x11800
	v_add_u32_e32 v232, s66, v198
	v_add_u32_e32 v233, s66, v200
	ds_read_b128 v[112:115], v232 offset:0
	ds_read_b128 v[116:119], v232 offset:4352
	ds_read_b128 v[120:123], v232 offset:64
	ds_read_b128 v[124:127], v232 offset:4416
	ds_read_b128 v[128:131], v232 offset:128
	ds_read_b128 v[132:135], v232 offset:4480
	ds_read_b128 v[136:139], v232 offset:192
	ds_read_b128 v[140:143], v232 offset:4544
	s_waitcnt lgkmcnt(6)
	v_mfma_f32_16x16x32_bf16 v[144:147], v[112:115], v[64:67], 0
	v_mfma_f32_16x16x32_bf16 v[148:151], v[116:119], v[64:67], 0
	v_add_u32_e32 v160, s78, v202
	ds_read_b32 v160, v160
	v_add_u32_e32 v161, s78, v203
	ds_read_b32 v161, v161
	v_add_u32_e32 v162, s78, v204
	ds_read_b32 v162, v162
	v_add_u32_e32 v163, s78, v205
	ds_read_b32 v163, v163
	v_add_u32_e32 v164, s78, v206
	ds_read_b32 v164, v164
	v_add_u32_e32 v165, s78, v207
	ds_read_b32 v165, v165
	v_add_u32_e32 v166, s78, v208
	ds_read_b32 v166, v166
	v_add_u32_e32 v167, s78, v209
	ds_read_b32 v167, v167
	s_waitcnt lgkmcnt(12)
	v_mfma_f32_16x16x32_bf16 v[144:147], v[120:123], v[68:71], v[144:147]
	v_mfma_f32_16x16x32_bf16 v[148:151], v[124:127], v[68:71], v[148:151]
	s_waitcnt lgkmcnt(10)
	v_mfma_f32_16x16x32_bf16 v[144:147], v[128:131], v[72:75], v[144:147]
	v_mfma_f32_16x16x32_bf16 v[148:151], v[132:135], v[72:75], v[148:151]
	s_waitcnt lgkmcnt(8)
	v_mfma_f32_16x16x32_bf16 v[144:147], v[136:139], v[76:79], v[144:147]
	v_mfma_f32_16x16x32_bf16 v[148:151], v[140:143], v[76:79], v[148:151]
	s_waitcnt lgkmcnt(0)
	v_add_u32_e32 v179, s79, v202
	ds_read_b32 v179, v179
	v_add_u32_e32 v180, s79, v203
	ds_read_b32 v180, v180
	v_add_u32_e32 v181, s79, v204
	ds_read_b32 v181, v181
	v_add_u32_e32 v182, s79, v205
	ds_read_b32 v182, v182
	v_add_u32_e32 v183, s79, v206
	ds_read_b32 v183, v183
	v_add_u32_e32 v184, s79, v207
	ds_read_b32 v184, v184
	v_add_u32_e32 v185, s79, v208
	ds_read_b32 v185, v185
	v_add_u32_e32 v186, s79, v209
	ds_read_b32 v186, v186
	v_mfma_f32_16x16x32_bf16 v[152:155], v[112:115], v[80:83], 0
	v_mfma_f32_16x16x32_bf16 v[156:159], v[116:119], v[80:83], 0
	ds_read_b64_tr_b16 v[112:113], v233 offset:0
	ds_read_b64_tr_b16 v[114:115], v233 offset:4608
	ds_read_b64_tr_b16 v[116:117], v233 offset:32
	ds_read_b64_tr_b16 v[118:119], v233 offset:4640
	v_fma_f32 v160, v144, s53, v160
	v_fma_f32 v161, v145, s53, v161
	v_fma_f32 v162, v146, s53, v162
	v_fma_f32 v163, v147, s53, v163
	v_fma_f32 v164, v148, s53, v164
	v_fma_f32 v165, v149, s53, v165
	v_fma_f32 v166, v150, s53, v166
	v_fma_f32 v167, v151, s53, v167
	v_max3_f32 v224, v160, v161, v162
	v_max3_f32 v224, v224, v163, v164
	v_mfma_f32_16x16x32_bf16 v[152:155], v[120:123], v[84:87], v[152:155]
	v_mfma_f32_16x16x32_bf16 v[156:159], v[124:127], v[84:87], v[156:159]
	s_waitcnt lgkmcnt(4)
	ds_read_b64_tr_b16 v[120:121], v233 offset:64
	ds_read_b64_tr_b16 v[122:123], v233 offset:4672
	ds_read_b64_tr_b16 v[124:125], v233 offset:96
	ds_read_b64_tr_b16 v[126:127], v233 offset:4704
	v_max3_f32 v224, v224, v165, v166
	v_max_f32_e32 v224, v224, v167
	v_cmp_gt_f32_e32 vcc, v224, v219
	s_cbranch_vccnz .Lna_rare_L_b0
.Lna_cont_L_b0:
	v_sub_f32_e32 v160, v160, v218
	v_sub_f32_e32 v161, v161, v218
	v_sub_f32_e32 v162, v162, v218
	v_sub_f32_e32 v163, v163, v218
	v_sub_f32_e32 v164, v164, v218
	v_sub_f32_e32 v165, v165, v218
	v_sub_f32_e32 v166, v166, v218
	v_mfma_f32_16x16x32_bf16 v[152:155], v[128:131], v[88:91], v[152:155]
	v_mfma_f32_16x16x32_bf16 v[156:159], v[132:135], v[88:91], v[156:159]
	ds_read_b64_tr_b16 v[128:129], v233 offset:128
	ds_read_b64_tr_b16 v[130:131], v233 offset:4736
	ds_read_b64_tr_b16 v[132:133], v233 offset:160
	ds_read_b64_tr_b16 v[134:135], v233 offset:4768
	v_sub_f32_e32 v167, v167, v218
	v_exp_f32_e32 v160, v160
	v_exp_f32_e32 v161, v161
	v_exp_f32_e32 v162, v162
	v_exp_f32_e32 v163, v163
	v_exp_f32_e32 v164, v164
	v_exp_f32_e32 v165, v165
	v_exp_f32_e32 v166, v166
	v_exp_f32_e32 v167, v167
	v_add_f32_e32 v224, v160, v161
	v_mfma_f32_16x16x32_bf16 v[152:155], v[136:139], v[92:95], v[152:155]
	v_mfma_f32_16x16x32_bf16 v[156:159], v[140:143], v[92:95], v[156:159]
	s_waitcnt lgkmcnt(8)
	ds_read_b64_tr_b16 v[136:137], v233 offset:192
	ds_read_b64_tr_b16 v[138:139], v233 offset:4800
	ds_read_b64_tr_b16 v[140:141], v233 offset:224
	ds_read_b64_tr_b16 v[142:143], v233 offset:4832
	v_add_f32_e32 v225, v162, v163
	v_add_f32_e32 v226, v164, v165
	v_add_f32_e32 v227, v166, v167
	v_add_f32_e32 v224, v224, v225
	v_add_f32_e32 v226, v226, v227
	v_add_f32_e32 v224, v224, v226
	v_add_f32_e32 v220, v220, v224
	v_cvt_pk_bf16_f32 v168, v160, v161
	v_cvt_pk_bf16_f32 v169, v162, v163
	v_cvt_pk_bf16_f32 v170, v164, v165
	v_cvt_pk_bf16_f32 v171, v166, v167
	s_nop 0
	s_waitcnt lgkmcnt(12)
	v_mfma_f32_16x16x32_bf16 v[0:3], v[112:115], v[168:171], v[0:3]
	v_fma_f32 v179, v152, s53, v179
	v_fma_f32 v180, v153, s53, v180
	v_fma_f32 v181, v154, s53, v181
	v_fma_f32 v182, v155, s53, v182
	v_fma_f32 v183, v156, s53, v183
	s_waitcnt lgkmcnt(12)
	v_mfma_f32_16x16x32_bf16 v[4:7], v[116:119], v[168:171], v[4:7]
	v_fma_f32 v184, v157, s53, v184
	v_fma_f32 v185, v158, s53, v185
	v_fma_f32 v186, v159, s53, v186
	v_max3_f32 v228, v179, v180, v181
	v_max3_f32 v228, v228, v182, v183
	s_waitcnt lgkmcnt(10)
	v_mfma_f32_16x16x32_bf16 v[8:11], v[120:123], v[168:171], v[8:11]
	v_max3_f32 v228, v228, v184, v185
	v_max_f32_e32 v228, v228, v186
	v_cmp_gt_f32_e32 vcc, v228, v222
	s_cbranch_vccnz .Lna_rare_L_b1
.Lna_cont_L_b1:
	v_sub_f32_e32 v179, v179, v221
	s_waitcnt lgkmcnt(8)
	v_mfma_f32_16x16x32_bf16 v[12:15], v[124:127], v[168:171], v[12:15]
	v_sub_f32_e32 v180, v180, v221
	v_sub_f32_e32 v181, v181, v221
	v_sub_f32_e32 v182, v182, v221
	v_sub_f32_e32 v183, v183, v221
	v_sub_f32_e32 v184, v184, v221
	v_sub_f32_e32 v185, v185, v221
	s_waitcnt lgkmcnt(6)
	v_mfma_f32_16x16x32_bf16 v[16:19], v[128:131], v[168:171], v[16:19]
	v_sub_f32_e32 v186, v186, v221
	v_exp_f32_e32 v179, v179
	v_exp_f32_e32 v180, v180
	v_exp_f32_e32 v181, v181
	v_exp_f32_e32 v182, v182
	s_waitcnt lgkmcnt(4)
	v_mfma_f32_16x16x32_bf16 v[20:23], v[132:135], v[168:171], v[20:23]
	v_exp_f32_e32 v183, v183
	v_exp_f32_e32 v184, v184
	v_exp_f32_e32 v185, v185
	v_exp_f32_e32 v186, v186
	v_add_f32_e32 v228, v179, v180
	s_waitcnt lgkmcnt(2)
	v_mfma_f32_16x16x32_bf16 v[24:27], v[136:139], v[168:171], v[24:27]
	v_add_f32_e32 v229, v181, v182
	v_add_f32_e32 v230, v183, v184
	v_add_f32_e32 v231, v185, v186
	v_add_f32_e32 v228, v228, v229
	v_add_f32_e32 v230, v230, v231
	s_waitcnt lgkmcnt(0)
	v_mfma_f32_16x16x32_bf16 v[28:31], v[140:143], v[168:171], v[28:31]
	v_add_f32_e32 v228, v228, v230
	v_add_f32_e32 v223, v223, v228
	v_cvt_pk_bf16_f32 v188, v179, v180
	v_cvt_pk_bf16_f32 v189, v181, v182
	v_cvt_pk_bf16_f32 v190, v183, v184
	v_cvt_pk_bf16_f32 v191, v185, v186
	s_nop 1
	v_mfma_f32_16x16x32_bf16 v[32:35], v[112:115], v[188:191], v[32:35]
	v_mfma_f32_16x16x32_bf16 v[36:39], v[116:119], v[188:191], v[36:39]
	v_mfma_f32_16x16x32_bf16 v[40:43], v[120:123], v[188:191], v[40:43]
	v_mfma_f32_16x16x32_bf16 v[44:47], v[124:127], v[188:191], v[44:47]
	v_mfma_f32_16x16x32_bf16 v[48:51], v[128:131], v[188:191], v[48:51]
	v_mfma_f32_16x16x32_bf16 v[52:55], v[132:135], v[188:191], v[52:55]
	v_mfma_f32_16x16x32_bf16 v[56:59], v[136:139], v[188:191], v[56:59]
	v_mfma_f32_16x16x32_bf16 v[60:63], v[140:143], v[188:191], v[60:63]
	s_branch .Lna_endcompute

.Lna_ctx_grp:
	ds_read_b128 v[112:115], v232 offset:0
	ds_read_b128 v[116:119], v232 offset:4352
	ds_read_b128 v[120:123], v232 offset:64
	ds_read_b128 v[124:127], v232 offset:4416
	ds_read_b128 v[128:131], v232 offset:128
	ds_read_b128 v[132:135], v232 offset:4480
	ds_read_b128 v[136:139], v232 offset:192
	ds_read_b128 v[140:143], v232 offset:4544
	s_waitcnt lgkmcnt(6)
	v_mfma_f32_16x16x32_bf16 v[144:147], v[112:115], v[64:67], 0
	v_mfma_f32_16x16x32_bf16 v[148:151], v[116:119], v[64:67], 0
	s_waitcnt lgkmcnt(4)
	v_mfma_f32_16x16x32_bf16 v[144:147], v[120:123], v[68:71], v[144:147]
	v_mfma_f32_16x16x32_bf16 v[148:151], v[124:127], v[68:71], v[148:151]
	s_waitcnt lgkmcnt(2)
	v_mfma_f32_16x16x32_bf16 v[144:147], v[128:131], v[72:75], v[144:147]
	v_mfma_f32_16x16x32_bf16 v[148:151], v[132:135], v[72:75], v[148:151]
	s_waitcnt lgkmcnt(0)
	v_mfma_f32_16x16x32_bf16 v[144:147], v[136:139], v[76:79], v[144:147]
	v_mfma_f32_16x16x32_bf16 v[148:151], v[140:143], v[76:79], v[148:151]
	v_mfma_f32_16x16x32_bf16 v[152:155], v[112:115], v[80:83], 0
	v_mfma_f32_16x16x32_bf16 v[156:159], v[116:119], v[80:83], 0
	ds_read_b64_tr_b16 v[112:113], v233 offset:0
	ds_read_b64_tr_b16 v[114:115], v233 offset:4608
	ds_read_b64_tr_b16 v[116:117], v233 offset:32
	ds_read_b64_tr_b16 v[118:119], v233 offset:4640
	s_nop 0
	v_fma_f32 v160, v144, s53, -v218
	v_fma_f32 v161, v145, s53, -v218
	v_fma_f32 v162, v146, s53, -v218
	v_fma_f32 v163, v147, s53, -v218
	v_fma_f32 v164, v148, s53, -v218
	v_fma_f32 v165, v149, s53, -v218
	v_fma_f32 v166, v150, s53, -v218
	v_fma_f32 v167, v151, s53, -v218
	v_mfma_f32_16x16x32_bf16 v[152:155], v[120:123], v[84:87], v[152:155]
	v_mfma_f32_16x16x32_bf16 v[156:159], v[124:127], v[84:87], v[156:159]
	ds_read_b64_tr_b16 v[120:121], v233 offset:64
	ds_read_b64_tr_b16 v[122:123], v233 offset:4672
	ds_read_b64_tr_b16 v[124:125], v233 offset:96
	ds_read_b64_tr_b16 v[126:127], v233 offset:4704
	v_max3_f32 v224, v160, v161, v162
	v_max3_f32 v224, v224, v163, v164
	v_max3_f32 v224, v224, v165, v166
	v_max_f32_e32 v224, v224, v167
	v_cmp_lt_f32_e32 vcc, 0x41000000, v224
	s_cbranch_vccnz .Lna_rare_C_b0
.Lna_cont_C_b0:
	v_exp_f32_e32 v160, v160
	v_exp_f32_e32 v161, v161
	v_exp_f32_e32 v162, v162
	v_mfma_f32_16x16x32_bf16 v[152:155], v[128:131], v[88:91], v[152:155]
	v_mfma_f32_16x16x32_bf16 v[156:159], v[132:135], v[88:91], v[156:159]
	ds_read_b64_tr_b16 v[128:129], v233 offset:128
	ds_read_b64_tr_b16 v[130:131], v233 offset:4736
	ds_read_b64_tr_b16 v[132:133], v233 offset:160
	ds_read_b64_tr_b16 v[134:135], v233 offset:4768
	v_exp_f32_e32 v163, v163
	v_exp_f32_e32 v164, v164
	v_exp_f32_e32 v165, v165
	v_exp_f32_e32 v166, v166
	v_exp_f32_e32 v167, v167
	v_add_f32_e32 v224, v160, v161
	v_add_f32_e32 v225, v162, v163
	v_add_f32_e32 v226, v164, v165
	v_mfma_f32_16x16x32_bf16 v[152:155], v[136:139], v[92:95], v[152:155]
	v_mfma_f32_16x16x32_bf16 v[156:159], v[140:143], v[92:95], v[156:159]
	s_waitcnt lgkmcnt(8)
	ds_read_b64_tr_b16 v[136:137], v233 offset:192
	ds_read_b64_tr_b16 v[138:139], v233 offset:4800
	ds_read_b64_tr_b16 v[140:141], v233 offset:224
	ds_read_b64_tr_b16 v[142:143], v233 offset:4832
	v_add_f32_e32 v227, v166, v167
	v_add_f32_e32 v224, v224, v225
	v_add_f32_e32 v226, v226, v227
	v_add_f32_e32 v224, v224, v226
	v_add_f32_e32 v220, v220, v224
	v_cvt_pk_bf16_f32 v168, v160, v161
	v_cvt_pk_bf16_f32 v169, v162, v163
	v_cvt_pk_bf16_f32 v170, v164, v165
	v_cvt_pk_bf16_f32 v171, v166, v167
	s_nop 0
	s_waitcnt lgkmcnt(12)
	v_mfma_f32_16x16x32_bf16 v[0:3], v[112:115], v[168:171], v[0:3]
	v_fma_f32 v179, v152, s53, -v221
	v_fma_f32 v180, v153, s53, -v221
	v_fma_f32 v181, v154, s53, -v221
	v_fma_f32 v182, v155, s53, -v221
	s_waitcnt lgkmcnt(12)
	v_mfma_f32_16x16x32_bf16 v[4:7], v[116:119], v[168:171], v[4:7]
	v_fma_f32 v183, v156, s53, -v221
	v_fma_f32 v184, v157, s53, -v221
	v_fma_f32 v185, v158, s53, -v221
	v_fma_f32 v186, v159, s53, -v221
	s_waitcnt lgkmcnt(10)
	v_mfma_f32_16x16x32_bf16 v[8:11], v[120:123], v[168:171], v[8:11]
	v_max3_f32 v228, v179, v180, v181
	v_max3_f32 v228, v228, v182, v183
	v_max3_f32 v228, v228, v184, v185
	v_max_f32_e32 v228, v228, v186
	s_waitcnt lgkmcnt(8)
	v_mfma_f32_16x16x32_bf16 v[12:15], v[124:127], v[168:171], v[12:15]
	v_cmp_lt_f32_e32 vcc, 0x41000000, v228
	s_cbranch_vccnz .Lna_rare_C_b1
.Lna_cont_C_b1:
	v_exp_f32_e32 v179, v179
	v_exp_f32_e32 v180, v180
	v_exp_f32_e32 v181, v181
	s_waitcnt lgkmcnt(6)
	v_mfma_f32_16x16x32_bf16 v[16:19], v[128:131], v[168:171], v[16:19]
	v_exp_f32_e32 v182, v182
	v_exp_f32_e32 v183, v183
	v_exp_f32_e32 v184, v184
	v_exp_f32_e32 v185, v185
	s_waitcnt lgkmcnt(4)
	v_mfma_f32_16x16x32_bf16 v[20:23], v[132:135], v[168:171], v[20:23]
	v_exp_f32_e32 v186, v186
	v_add_f32_e32 v228, v179, v180
	v_add_f32_e32 v229, v181, v182
	v_add_f32_e32 v230, v183, v184
	s_waitcnt lgkmcnt(2)
	v_mfma_f32_16x16x32_bf16 v[24:27], v[136:139], v[168:171], v[24:27]
	v_add_f32_e32 v231, v185, v186
	v_add_f32_e32 v228, v228, v229
	v_add_f32_e32 v230, v230, v231
	v_add_f32_e32 v228, v228, v230
	s_waitcnt lgkmcnt(0)
	v_mfma_f32_16x16x32_bf16 v[28:31], v[140:143], v[168:171], v[28:31]
	v_add_f32_e32 v223, v223, v228
	v_cvt_pk_bf16_f32 v188, v179, v180
	v_cvt_pk_bf16_f32 v189, v181, v182
	v_cvt_pk_bf16_f32 v190, v183, v184
	v_cvt_pk_bf16_f32 v191, v185, v186
	s_nop 1
	v_mfma_f32_16x16x32_bf16 v[32:35], v[112:115], v[188:191], v[32:35]
	v_mfma_f32_16x16x32_bf16 v[36:39], v[116:119], v[188:191], v[36:39]
	v_mfma_f32_16x16x32_bf16 v[40:43], v[120:123], v[188:191], v[40:43]
	v_mfma_f32_16x16x32_bf16 v[44:47], v[124:127], v[188:191], v[44:47]
	v_mfma_f32_16x16x32_bf16 v[48:51], v[128:131], v[188:191], v[48:51]
	v_mfma_f32_16x16x32_bf16 v[52:55], v[132:135], v[188:191], v[52:55]
	v_mfma_f32_16x16x32_bf16 v[56:59], v[136:139], v[188:191], v[56:59]
	v_mfma_f32_16x16x32_bf16 v[60:63], v[140:143], v[188:191], v[60:63]
	v_add_u32_e32 v232, 0x2200, v232
	v_add_u32_e32 v233, 0x2400, v233
	s_add_u32 s90, s90, 1
	s_cmp_lt_u32 s90, 2
	s_cbranch_scc1 .Lna_ctx_grp
.Lna_endcompute:
	s_cmp_eq_u32 s67, 0
	s_cbranch_scc1 .Lna_nostore
	s_sub_u32 s1, 0x8c00, s66
	v_add_u32_e32 v234, s1, v196
	v_add_u32_e32 v235, s1, v197
	s_waitcnt vmcnt(0)
	ds_write_b128 v234, v[96:99]
	ds_write_b128 v235, v[100:103]
	ds_write_b128 v234, v[104:107] offset:8704
	ds_write_b128 v235, v[108:111] offset:9216
.Lna_nostore:
	s_waitcnt lgkmcnt(0)
	s_barrier
	s_sub_u32 s66, 0x8c00, s66
	s_add_u32 s52, s52, 1
	s_cmp_lt_u32 s52, s51
	s_cbranch_scc1 .Lna_it
	s_lshl_b32 s6, s43, 8
	s_lshl_b32 s7, s8, 15
	s_add_u32 s7, s7, s6
	s_add_u32 s7, s7, 0x6000
	s_add_u32 s72, s26, s7
	s_addc_u32 s73, s27, 0
	s_lshl_b32 s7, s8, 13
	s_add_u32 s7, s7, s6
	s_add_u32 s12, s28, s7
	s_addc_u32 s13, s29, 0
	global_load_dwordx4 v[112:115], v211, s[72:73] offset:0
	global_load_dwordx4 v[116:119], v211, s[72:73] offset:64
	global_load_dwordx4 v[120:123], v211, s[72:73] offset:128
	global_load_dwordx4 v[124:127], v211, s[72:73] offset:192
	s_lshl_b32 s7, s9, 15
	s_add_u32 s7, s7, s6
	s_add_u32 s7, s7, 0x6000
	s_add_u32 s16, s26, s7
	s_addc_u32 s17, s27, 0
	s_lshl_b32 s7, s9, 13
	s_add_u32 s7, s7, s6
	s_add_u32 s30, s28, s7
	s_addc_u32 s31, s29, 0
	global_load_dwordx4 v[128:131], v211, s[16:17] offset:0
	global_load_dwordx4 v[132:135], v211, s[16:17] offset:64
	global_load_dwordx4 v[136:139], v211, s[16:17] offset:128
	global_load_dwordx4 v[140:143], v211, s[16:17] offset:192
	s_add_u32 s15, s40, s94
	s_cmp_lt_u32 s15, s41
	s_cselect_b32 s40, s15, s40
	s_cmp_ge_u32 s40, 0x400
	s_cbranch_scc1 .Lna_dec_ctx_1
	s_mov_b32 s45, 0
	s_cmp_eq_u32 s94, 0x100
	s_cbranch_scc0 .Lna_dec_gen_1
	s_lshr_b32 s1, s40, 8
	s_and_b32 s2, s40, 0xff
	s_lshl_b32 s1, s1, 5
	s_and_b32 s4, s2, 7
	s_lshl_b32 s4, s4, 2
	s_add_u32 s1, s1, s4
	s_lshr_b32 s4, s2, 6
	s_add_u32 s1, s1, s4
	s_bfe_u32 s44, s2, 0x30003
	s_branch .Lna_dec_l2_1

.Lna_tb_done2:
	s_lshl_b32 s1, s1, 15
	s_lshl_b32 s2, s43, 8
	s_add_u32 s1, s1, s2
	s_add_u32 s1, s1, 0x2000
	s_add_u32 s54, s26, s1
	s_addc_u32 s55, s27, 0
	s_add_u32 s56, s54, 0x2000
	s_addc_u32 s57, s55, 0
	global_load_dwordx4 v[96:99], v194, s[54:55]
	global_load_dwordx4 v[100:103], v194, s[56:57]
	global_load_dwordx4 v[104:107], v195, s[54:55]
	global_load_dwordx4 v[108:111], v195, s[56:57]
	s_mov_b32 s4, 0xbfb8aa3b
	s_mov_b32 s5, 0xbfb8aa3b
	ds_bpermute_b32 v224, v215, v220
	s_waitcnt lgkmcnt(0)
	v_add_f32_e32 v220, v220, v224
	ds_bpermute_b32 v224, v216, v220
	s_waitcnt lgkmcnt(0)
	v_add_f32_e32 v224, v220, v224
	v_mov_b32_e32 v225, v224
	s_waitcnt vmcnt(17)
	v_permlane16_swap_b32_e32 v112, v114
	v_permlane16_swap_b32_e32 v113, v115
	v_lshlrev_b32_e32 v226, 16, v112
	v_and_b32_e32 v227, 0xffff0000, v112
	v_lshlrev_b32_e32 v228, 16, v113
	v_and_b32_e32 v229, 0xffff0000, v113
	v_pk_mul_f32 v[230:231], v[226:227], s[4:5]
	v_pk_mul_f32 v[160:161], v[228:229], s[4:5]
	v_exp_f32_e32 v230, v230
	v_exp_f32_e32 v231, v231
	v_exp_f32_e32 v160, v160
	v_exp_f32_e32 v161, v161
	v_pk_mul_f32 v[0:1], v[0:1], v[226:227]
	v_pk_mul_f32 v[2:3], v[2:3], v[228:229]
	v_pk_fma_f32 v[230:231], v[230:231], v[224:225], v[224:225]
	v_pk_fma_f32 v[160:161], v[160:161], v[224:225], v[224:225]
	v_rcp_f32_e32 v230, v230
	v_rcp_f32_e32 v231, v231
	v_rcp_f32_e32 v160, v160
	v_rcp_f32_e32 v161, v161
	s_nop 0
	v_pk_mul_f32 v[0:1], v[0:1], v[230:231]
	v_pk_mul_f32 v[2:3], v[2:3], v[160:161]
	v_lshlrev_b32_e32 v226, 16, v114
	v_and_b32_e32 v227, 0xffff0000, v114
	v_lshlrev_b32_e32 v228, 16, v115
	v_and_b32_e32 v229, 0xffff0000, v115
	v_pk_mul_f32 v[230:231], v[226:227], s[4:5]
	v_pk_mul_f32 v[160:161], v[228:229], s[4:5]
	v_exp_f32_e32 v230, v230
	v_exp_f32_e32 v231, v231
	v_exp_f32_e32 v160, v160
	v_exp_f32_e32 v161, v161
	v_pk_mul_f32 v[4:5], v[4:5], v[226:227]
	v_pk_mul_f32 v[6:7], v[6:7], v[228:229]
	v_pk_fma_f32 v[230:231], v[230:231], v[224:225], v[224:225]
	v_pk_fma_f32 v[160:161], v[160:161], v[224:225], v[224:225]
	v_rcp_f32_e32 v230, v230
	v_rcp_f32_e32 v231, v231
	v_rcp_f32_e32 v160, v160
	v_rcp_f32_e32 v161, v161
	s_nop 0
	v_pk_mul_f32 v[4:5], v[4:5], v[230:231]
	v_pk_mul_f32 v[6:7], v[6:7], v[160:161]
	v_cvt_pk_bf16_f32 v0, v0, v1
	v_cvt_pk_bf16_f32 v1, v2, v3
	v_cvt_pk_bf16_f32 v2, v4, v5
	v_cvt_pk_bf16_f32 v3, v6, v7
	s_nop 1
	v_permlane16_swap_b32_e32 v0, v2
	v_permlane16_swap_b32_e32 v1, v3
	global_store_dwordx4 v212, v[0:3], s[12:13] offset:0
	v_permlane16_swap_b32_e32 v116, v118
	v_permlane16_swap_b32_e32 v117, v119
	v_lshlrev_b32_e32 v226, 16, v116
	v_and_b32_e32 v227, 0xffff0000, v116
	v_lshlrev_b32_e32 v228, 16, v117
	v_and_b32_e32 v229, 0xffff0000, v117
	v_pk_mul_f32 v[230:231], v[226:227], s[4:5]
	v_pk_mul_f32 v[160:161], v[228:229], s[4:5]
	v_exp_f32_e32 v230, v230
	v_exp_f32_e32 v231, v231
	v_exp_f32_e32 v160, v160
	v_exp_f32_e32 v161, v161
	v_pk_mul_f32 v[8:9], v[8:9], v[226:227]
	v_pk_mul_f32 v[10:11], v[10:11], v[228:229]
	v_pk_fma_f32 v[230:231], v[230:231], v[224:225], v[224:225]
	v_pk_fma_f32 v[160:161], v[160:161], v[224:225], v[224:225]
	v_rcp_f32_e32 v230, v230
	v_rcp_f32_e32 v231, v231
	v_rcp_f32_e32 v160, v160
	v_rcp_f32_e32 v161, v161
	s_nop 0
	v_pk_mul_f32 v[8:9], v[8:9], v[230:231]
	v_pk_mul_f32 v[10:11], v[10:11], v[160:161]
	v_lshlrev_b32_e32 v226, 16, v118
	v_and_b32_e32 v227, 0xffff0000, v118
	v_lshlrev_b32_e32 v228, 16, v119
	v_and_b32_e32 v229, 0xffff0000, v119
	v_pk_mul_f32 v[230:231], v[226:227], s[4:5]
	v_pk_mul_f32 v[160:161], v[228:229], s[4:5]
	v_exp_f32_e32 v230, v230
	v_exp_f32_e32 v231, v231
	v_exp_f32_e32 v160, v160
	v_exp_f32_e32 v161, v161
	v_pk_mul_f32 v[12:13], v[12:13], v[226:227]
	v_pk_mul_f32 v[14:15], v[14:15], v[228:229]
	v_pk_fma_f32 v[230:231], v[230:231], v[224:225], v[224:225]
	v_pk_fma_f32 v[160:161], v[160:161], v[224:225], v[224:225]
	v_rcp_f32_e32 v230, v230
	v_rcp_f32_e32 v231, v231
	v_rcp_f32_e32 v160, v160
	v_rcp_f32_e32 v161, v161
	s_nop 0
	v_pk_mul_f32 v[12:13], v[12:13], v[230:231]
	v_pk_mul_f32 v[14:15], v[14:15], v[160:161]
	v_cvt_pk_bf16_f32 v8, v8, v9
	v_cvt_pk_bf16_f32 v9, v10, v11
	v_cvt_pk_bf16_f32 v10, v12, v13
	v_cvt_pk_bf16_f32 v11, v14, v15
	s_nop 1
	v_permlane16_swap_b32_e32 v8, v10
	v_permlane16_swap_b32_e32 v9, v11
	global_store_dwordx4 v212, v[8:11], s[12:13] offset:64
	v_permlane16_swap_b32_e32 v120, v122
	v_permlane16_swap_b32_e32 v121, v123
	v_lshlrev_b32_e32 v226, 16, v120
	v_and_b32_e32 v227, 0xffff0000, v120
	v_lshlrev_b32_e32 v228, 16, v121
	v_and_b32_e32 v229, 0xffff0000, v121
	v_pk_mul_f32 v[230:231], v[226:227], s[4:5]
	v_pk_mul_f32 v[160:161], v[228:229], s[4:5]
	v_exp_f32_e32 v230, v230
	v_exp_f32_e32 v231, v231
	v_exp_f32_e32 v160, v160
	v_exp_f32_e32 v161, v161
	v_pk_mul_f32 v[16:17], v[16:17], v[226:227]
	v_pk_mul_f32 v[18:19], v[18:19], v[228:229]
	v_pk_fma_f32 v[230:231], v[230:231], v[224:225], v[224:225]
	v_pk_fma_f32 v[160:161], v[160:161], v[224:225], v[224:225]
	v_rcp_f32_e32 v230, v230
	v_rcp_f32_e32 v231, v231
	v_rcp_f32_e32 v160, v160
	v_rcp_f32_e32 v161, v161
	s_nop 0
	v_pk_mul_f32 v[16:17], v[16:17], v[230:231]
	v_pk_mul_f32 v[18:19], v[18:19], v[160:161]
	v_lshlrev_b32_e32 v226, 16, v122
	v_and_b32_e32 v227, 0xffff0000, v122
	v_lshlrev_b32_e32 v228, 16, v123
	v_and_b32_e32 v229, 0xffff0000, v123
	v_pk_mul_f32 v[230:231], v[226:227], s[4:5]
	v_pk_mul_f32 v[160:161], v[228:229], s[4:5]
	v_exp_f32_e32 v230, v230
	v_exp_f32_e32 v231, v231
	v_exp_f32_e32 v160, v160
	v_exp_f32_e32 v161, v161
	v_pk_mul_f32 v[20:21], v[20:21], v[226:227]
	v_pk_mul_f32 v[22:23], v[22:23], v[228:229]
	v_pk_fma_f32 v[230:231], v[230:231], v[224:225], v[224:225]
	v_pk_fma_f32 v[160:161], v[160:161], v[224:225], v[224:225]
	v_rcp_f32_e32 v230, v230
	v_rcp_f32_e32 v231, v231
	v_rcp_f32_e32 v160, v160
	v_rcp_f32_e32 v161, v161
	s_nop 0
	v_pk_mul_f32 v[20:21], v[20:21], v[230:231]
	v_pk_mul_f32 v[22:23], v[22:23], v[160:161]
	v_cvt_pk_bf16_f32 v16, v16, v17
	v_cvt_pk_bf16_f32 v17, v18, v19
	v_cvt_pk_bf16_f32 v18, v20, v21
	v_cvt_pk_bf16_f32 v19, v22, v23
	s_nop 1
	v_permlane16_swap_b32_e32 v16, v18
	v_permlane16_swap_b32_e32 v17, v19
	global_store_dwordx4 v212, v[16:19], s[12:13] offset:128
	v_permlane16_swap_b32_e32 v124, v126
	v_permlane16_swap_b32_e32 v125, v127
	v_lshlrev_b32_e32 v226, 16, v124
	v_and_b32_e32 v227, 0xffff0000, v124
	v_lshlrev_b32_e32 v228, 16, v125
	v_and_b32_e32 v229, 0xffff0000, v125
	v_pk_mul_f32 v[230:231], v[226:227], s[4:5]
	v_pk_mul_f32 v[160:161], v[228:229], s[4:5]
	v_exp_f32_e32 v230, v230
	v_exp_f32_e32 v231, v231
	v_exp_f32_e32 v160, v160
	v_exp_f32_e32 v161, v161
	v_pk_mul_f32 v[24:25], v[24:25], v[226:227]
	v_pk_mul_f32 v[26:27], v[26:27], v[228:229]
	v_pk_fma_f32 v[230:231], v[230:231], v[224:225], v[224:225]
	v_pk_fma_f32 v[160:161], v[160:161], v[224:225], v[224:225]
	v_rcp_f32_e32 v230, v230
	v_rcp_f32_e32 v231, v231
	v_rcp_f32_e32 v160, v160
	v_rcp_f32_e32 v161, v161
	s_nop 0
	v_pk_mul_f32 v[24:25], v[24:25], v[230:231]
	v_pk_mul_f32 v[26:27], v[26:27], v[160:161]
	v_lshlrev_b32_e32 v226, 16, v126
	v_and_b32_e32 v227, 0xffff0000, v126
	v_lshlrev_b32_e32 v228, 16, v127
	v_and_b32_e32 v229, 0xffff0000, v127
	v_pk_mul_f32 v[230:231], v[226:227], s[4:5]
	v_pk_mul_f32 v[160:161], v[228:229], s[4:5]
	v_exp_f32_e32 v230, v230
	v_exp_f32_e32 v231, v231
	v_exp_f32_e32 v160, v160
	v_exp_f32_e32 v161, v161
	v_pk_mul_f32 v[28:29], v[28:29], v[226:227]
	v_pk_mul_f32 v[30:31], v[30:31], v[228:229]
	v_pk_fma_f32 v[230:231], v[230:231], v[224:225], v[224:225]
	v_pk_fma_f32 v[160:161], v[160:161], v[224:225], v[224:225]
	v_rcp_f32_e32 v230, v230
	v_rcp_f32_e32 v231, v231
	v_rcp_f32_e32 v160, v160
	v_rcp_f32_e32 v161, v161
	s_nop 0
	v_pk_mul_f32 v[28:29], v[28:29], v[230:231]
	v_pk_mul_f32 v[30:31], v[30:31], v[160:161]
	v_cvt_pk_bf16_f32 v24, v24, v25
	v_cvt_pk_bf16_f32 v25, v26, v27
	v_cvt_pk_bf16_f32 v26, v28, v29
	v_cvt_pk_bf16_f32 v27, v30, v31
	s_nop 1
	v_permlane16_swap_b32_e32 v24, v26
	v_permlane16_swap_b32_e32 v25, v27
	global_store_dwordx4 v212, v[24:27], s[12:13] offset:192
	ds_bpermute_b32 v224, v215, v223
	s_waitcnt lgkmcnt(0)
	v_add_f32_e32 v223, v223, v224
	ds_bpermute_b32 v224, v216, v223
	s_waitcnt lgkmcnt(0)
	v_add_f32_e32 v224, v223, v224
	v_mov_b32_e32 v225, v224
	s_waitcnt vmcnt(17)
	v_permlane16_swap_b32_e32 v128, v130
	v_permlane16_swap_b32_e32 v129, v131
	v_lshlrev_b32_e32 v226, 16, v128
	v_and_b32_e32 v227, 0xffff0000, v128
	v_lshlrev_b32_e32 v228, 16, v129
	v_and_b32_e32 v229, 0xffff0000, v129
	v_pk_mul_f32 v[230:231], v[226:227], s[4:5]
	v_pk_mul_f32 v[160:161], v[228:229], s[4:5]
	v_exp_f32_e32 v230, v230
	v_exp_f32_e32 v231, v231
	v_exp_f32_e32 v160, v160
	v_exp_f32_e32 v161, v161
	v_pk_mul_f32 v[32:33], v[32:33], v[226:227]
	v_pk_mul_f32 v[34:35], v[34:35], v[228:229]
	v_pk_fma_f32 v[230:231], v[230:231], v[224:225], v[224:225]
	v_pk_fma_f32 v[160:161], v[160:161], v[224:225], v[224:225]
	v_rcp_f32_e32 v230, v230
	v_rcp_f32_e32 v231, v231
	v_rcp_f32_e32 v160, v160
	v_rcp_f32_e32 v161, v161
	s_nop 0
	v_pk_mul_f32 v[32:33], v[32:33], v[230:231]
	v_pk_mul_f32 v[34:35], v[34:35], v[160:161]
	v_lshlrev_b32_e32 v226, 16, v130
	v_and_b32_e32 v227, 0xffff0000, v130
	v_lshlrev_b32_e32 v228, 16, v131
	v_and_b32_e32 v229, 0xffff0000, v131
	v_pk_mul_f32 v[230:231], v[226:227], s[4:5]
	v_pk_mul_f32 v[160:161], v[228:229], s[4:5]
	v_exp_f32_e32 v230, v230
	v_exp_f32_e32 v231, v231
	v_exp_f32_e32 v160, v160
	v_exp_f32_e32 v161, v161
	v_pk_mul_f32 v[36:37], v[36:37], v[226:227]
	v_pk_mul_f32 v[38:39], v[38:39], v[228:229]
	v_pk_fma_f32 v[230:231], v[230:231], v[224:225], v[224:225]
	v_pk_fma_f32 v[160:161], v[160:161], v[224:225], v[224:225]
	v_rcp_f32_e32 v230, v230
	v_rcp_f32_e32 v231, v231
	v_rcp_f32_e32 v160, v160
	v_rcp_f32_e32 v161, v161
	s_nop 0
	v_pk_mul_f32 v[36:37], v[36:37], v[230:231]
	v_pk_mul_f32 v[38:39], v[38:39], v[160:161]
	v_cvt_pk_bf16_f32 v32, v32, v33
	v_cvt_pk_bf16_f32 v33, v34, v35
	v_cvt_pk_bf16_f32 v34, v36, v37
	v_cvt_pk_bf16_f32 v35, v38, v39
	s_nop 1
	v_permlane16_swap_b32_e32 v32, v34
	v_permlane16_swap_b32_e32 v33, v35
	global_store_dwordx4 v212, v[32:35], s[30:31] offset:0
	v_permlane16_swap_b32_e32 v132, v134
	v_permlane16_swap_b32_e32 v133, v135
	v_lshlrev_b32_e32 v226, 16, v132
	v_and_b32_e32 v227, 0xffff0000, v132
	v_lshlrev_b32_e32 v228, 16, v133
	v_and_b32_e32 v229, 0xffff0000, v133
	v_pk_mul_f32 v[230:231], v[226:227], s[4:5]
	v_pk_mul_f32 v[160:161], v[228:229], s[4:5]
	v_exp_f32_e32 v230, v230
	v_exp_f32_e32 v231, v231
	v_exp_f32_e32 v160, v160
	v_exp_f32_e32 v161, v161
	v_pk_mul_f32 v[40:41], v[40:41], v[226:227]
	v_pk_mul_f32 v[42:43], v[42:43], v[228:229]
	v_pk_fma_f32 v[230:231], v[230:231], v[224:225], v[224:225]
	v_pk_fma_f32 v[160:161], v[160:161], v[224:225], v[224:225]
	v_rcp_f32_e32 v230, v230
	v_rcp_f32_e32 v231, v231
	v_rcp_f32_e32 v160, v160
	v_rcp_f32_e32 v161, v161
	s_nop 0
	v_pk_mul_f32 v[40:41], v[40:41], v[230:231]
	v_pk_mul_f32 v[42:43], v[42:43], v[160:161]
	v_lshlrev_b32_e32 v226, 16, v134
	v_and_b32_e32 v227, 0xffff0000, v134
	v_lshlrev_b32_e32 v228, 16, v135
	v_and_b32_e32 v229, 0xffff0000, v135
	v_pk_mul_f32 v[230:231], v[226:227], s[4:5]
	v_pk_mul_f32 v[160:161], v[228:229], s[4:5]
	v_exp_f32_e32 v230, v230
	v_exp_f32_e32 v231, v231
	v_exp_f32_e32 v160, v160
	v_exp_f32_e32 v161, v161
	v_pk_mul_f32 v[44:45], v[44:45], v[226:227]
	v_pk_mul_f32 v[46:47], v[46:47], v[228:229]
	v_pk_fma_f32 v[230:231], v[230:231], v[224:225], v[224:225]
	v_pk_fma_f32 v[160:161], v[160:161], v[224:225], v[224:225]
	v_rcp_f32_e32 v230, v230
	v_rcp_f32_e32 v231, v231
	v_rcp_f32_e32 v160, v160
	v_rcp_f32_e32 v161, v161
	s_nop 0
	v_pk_mul_f32 v[44:45], v[44:45], v[230:231]
	v_pk_mul_f32 v[46:47], v[46:47], v[160:161]
	v_cvt_pk_bf16_f32 v40, v40, v41
	v_cvt_pk_bf16_f32 v41, v42, v43
	v_cvt_pk_bf16_f32 v42, v44, v45
	v_cvt_pk_bf16_f32 v43, v46, v47
	s_nop 1
	v_permlane16_swap_b32_e32 v40, v42
	v_permlane16_swap_b32_e32 v41, v43
	global_store_dwordx4 v212, v[40:43], s[30:31] offset:64
	v_permlane16_swap_b32_e32 v136, v138
	v_permlane16_swap_b32_e32 v137, v139
	v_lshlrev_b32_e32 v226, 16, v136
	v_and_b32_e32 v227, 0xffff0000, v136
	v_lshlrev_b32_e32 v228, 16, v137
	v_and_b32_e32 v229, 0xffff0000, v137
	v_pk_mul_f32 v[230:231], v[226:227], s[4:5]
	v_pk_mul_f32 v[160:161], v[228:229], s[4:5]
	v_exp_f32_e32 v230, v230
	v_exp_f32_e32 v231, v231
	v_exp_f32_e32 v160, v160
	v_exp_f32_e32 v161, v161
	v_pk_mul_f32 v[48:49], v[48:49], v[226:227]
	v_pk_mul_f32 v[50:51], v[50:51], v[228:229]
	v_pk_fma_f32 v[230:231], v[230:231], v[224:225], v[224:225]
	v_pk_fma_f32 v[160:161], v[160:161], v[224:225], v[224:225]
	v_rcp_f32_e32 v230, v230
	v_rcp_f32_e32 v231, v231
	v_rcp_f32_e32 v160, v160
	v_rcp_f32_e32 v161, v161
	s_nop 0
	v_pk_mul_f32 v[48:49], v[48:49], v[230:231]
	v_pk_mul_f32 v[50:51], v[50:51], v[160:161]
	v_lshlrev_b32_e32 v226, 16, v138
	v_and_b32_e32 v227, 0xffff0000, v138
	v_lshlrev_b32_e32 v228, 16, v139
	v_and_b32_e32 v229, 0xffff0000, v139
	v_pk_mul_f32 v[230:231], v[226:227], s[4:5]
	v_pk_mul_f32 v[160:161], v[228:229], s[4:5]
	v_exp_f32_e32 v230, v230
	v_exp_f32_e32 v231, v231
	v_exp_f32_e32 v160, v160
	v_exp_f32_e32 v161, v161
	v_pk_mul_f32 v[52:53], v[52:53], v[226:227]
	v_pk_mul_f32 v[54:55], v[54:55], v[228:229]
	v_pk_fma_f32 v[230:231], v[230:231], v[224:225], v[224:225]
	v_pk_fma_f32 v[160:161], v[160:161], v[224:225], v[224:225]
	v_rcp_f32_e32 v230, v230
	v_rcp_f32_e32 v231, v231
	v_rcp_f32_e32 v160, v160
	v_rcp_f32_e32 v161, v161
	s_nop 0
	v_pk_mul_f32 v[52:53], v[52:53], v[230:231]
	v_pk_mul_f32 v[54:55], v[54:55], v[160:161]
	v_cvt_pk_bf16_f32 v48, v48, v49
	v_cvt_pk_bf16_f32 v49, v50, v51
	v_cvt_pk_bf16_f32 v50, v52, v53
	v_cvt_pk_bf16_f32 v51, v54, v55
	s_nop 1
	v_permlane16_swap_b32_e32 v48, v50
	v_permlane16_swap_b32_e32 v49, v51
	global_store_dwordx4 v212, v[48:51], s[30:31] offset:128
	v_permlane16_swap_b32_e32 v140, v142
	v_permlane16_swap_b32_e32 v141, v143
	v_lshlrev_b32_e32 v226, 16, v140
	v_and_b32_e32 v227, 0xffff0000, v140
	v_lshlrev_b32_e32 v228, 16, v141
	v_and_b32_e32 v229, 0xffff0000, v141
	v_pk_mul_f32 v[230:231], v[226:227], s[4:5]
	v_pk_mul_f32 v[160:161], v[228:229], s[4:5]
	v_exp_f32_e32 v230, v230
	v_exp_f32_e32 v231, v231
	v_exp_f32_e32 v160, v160
	v_exp_f32_e32 v161, v161
	v_pk_mul_f32 v[56:57], v[56:57], v[226:227]
	v_pk_mul_f32 v[58:59], v[58:59], v[228:229]
	v_pk_fma_f32 v[230:231], v[230:231], v[224:225], v[224:225]
	v_pk_fma_f32 v[160:161], v[160:161], v[224:225], v[224:225]
	v_rcp_f32_e32 v230, v230
	v_rcp_f32_e32 v231, v231
	v_rcp_f32_e32 v160, v160
	v_rcp_f32_e32 v161, v161
	s_nop 0
	v_pk_mul_f32 v[56:57], v[56:57], v[230:231]
	v_pk_mul_f32 v[58:59], v[58:59], v[160:161]
	v_lshlrev_b32_e32 v226, 16, v142
	v_and_b32_e32 v227, 0xffff0000, v142
	v_lshlrev_b32_e32 v228, 16, v143
	v_and_b32_e32 v229, 0xffff0000, v143
	v_pk_mul_f32 v[230:231], v[226:227], s[4:5]
	v_pk_mul_f32 v[160:161], v[228:229], s[4:5]
	v_exp_f32_e32 v230, v230
	v_exp_f32_e32 v231, v231
	v_exp_f32_e32 v160, v160
	v_exp_f32_e32 v161, v161
	v_pk_mul_f32 v[60:61], v[60:61], v[226:227]
	v_pk_mul_f32 v[62:63], v[62:63], v[228:229]
	v_pk_fma_f32 v[230:231], v[230:231], v[224:225], v[224:225]
	v_pk_fma_f32 v[160:161], v[160:161], v[224:225], v[224:225]
	v_rcp_f32_e32 v230, v230
	v_rcp_f32_e32 v231, v231
	v_rcp_f32_e32 v160, v160
	v_rcp_f32_e32 v161, v161
	s_nop 0
	v_pk_mul_f32 v[60:61], v[60:61], v[230:231]
	v_pk_mul_f32 v[62:63], v[62:63], v[160:161]
	v_cvt_pk_bf16_f32 v56, v56, v57
	v_cvt_pk_bf16_f32 v57, v58, v59
	v_cvt_pk_bf16_f32 v58, v60, v61
	v_cvt_pk_bf16_f32 v59, v62, v63
	s_nop 1
	v_permlane16_swap_b32_e32 v56, v58
	v_permlane16_swap_b32_e32 v57, v59
	global_store_dwordx4 v212, v[56:59], s[30:31] offset:192
	s_cmp_lt_u32 s15, s41
	s_cbranch_scc1 .Lna_unit_next
	s_branch .Lna_done

.Lna_rare_L_b1:
	ds_bpermute_b32 v229, v215, v228
	ds_bpermute_b32 v230, v216, v228
	ds_bpermute_b32 v231, v217, v228
	s_waitcnt lgkmcnt(0)
	v_max3_f32 v228, v228, v229, v230
	v_max_f32_e32 v228, v228, v231
	v_max_f32_e32 v229, v221, v228
	v_sub_f32_e32 v230, v221, v229
	v_exp_f32_e32 v230, v230
	v_mov_b32_e32 v221, v229
	v_add_f32_e32 v222, 0x41000000, v229
	v_mul_f32_e32 v223, v223, v230
	v_mul_f32_e32 v32, v32, v230
	v_mul_f32_e32 v33, v33, v230
	v_mul_f32_e32 v34, v34, v230
	v_mul_f32_e32 v35, v35, v230
	v_mul_f32_e32 v36, v36, v230
	v_mul_f32_e32 v37, v37, v230
	v_mul_f32_e32 v38, v38, v230
	v_mul_f32_e32 v39, v39, v230
	v_mul_f32_e32 v40, v40, v230
	v_mul_f32_e32 v41, v41, v230
	v_mul_f32_e32 v42, v42, v230
	v_mul_f32_e32 v43, v43, v230
	v_mul_f32_e32 v44, v44, v230
	v_mul_f32_e32 v45, v45, v230
	v_mul_f32_e32 v46, v46, v230
	v_mul_f32_e32 v47, v47, v230
	v_mul_f32_e32 v48, v48, v230
	v_mul_f32_e32 v49, v49, v230
	v_mul_f32_e32 v50, v50, v230
	v_mul_f32_e32 v51, v51, v230
	v_mul_f32_e32 v52, v52, v230
	v_mul_f32_e32 v53, v53, v230
	v_mul_f32_e32 v54, v54, v230
	v_mul_f32_e32 v55, v55, v230
	v_mul_f32_e32 v56, v56, v230
	v_mul_f32_e32 v57, v57, v230
	v_mul_f32_e32 v58, v58, v230
	v_mul_f32_e32 v59, v59, v230
	v_mul_f32_e32 v60, v60, v230
	v_mul_f32_e32 v61, v61, v230
	v_mul_f32_e32 v62, v62, v230
	v_mul_f32_e32 v63, v63, v230
	s_branch .Lna_cont_L_b1

.Lna_rare_C_b1:
	v_mul_f32_e32 v179, s53, v152
	v_mul_f32_e32 v180, s53, v153
	v_mul_f32_e32 v181, s53, v154
	v_mul_f32_e32 v182, s53, v155
	v_mul_f32_e32 v183, s53, v156
	v_mul_f32_e32 v184, s53, v157
	v_mul_f32_e32 v185, s53, v158
	v_mul_f32_e32 v186, s53, v159
	v_max3_f32 v228, v179, v180, v181
	v_max3_f32 v228, v228, v182, v183
	v_max3_f32 v228, v228, v184, v185
	v_max_f32_e32 v228, v228, v186
	ds_bpermute_b32 v229, v215, v228
	ds_bpermute_b32 v230, v216, v228
	ds_bpermute_b32 v231, v217, v228
	s_waitcnt lgkmcnt(0)
	v_max3_f32 v228, v228, v229, v230
	v_max_f32_e32 v228, v228, v231
	v_max_f32_e32 v229, v221, v228
	v_sub_f32_e32 v230, v221, v229
	v_exp_f32_e32 v230, v230
	v_mov_b32_e32 v221, v229
	v_add_f32_e32 v222, 0x41000000, v229
	v_mul_f32_e32 v223, v223, v230
	v_mul_f32_e32 v32, v32, v230
	v_mul_f32_e32 v33, v33, v230
	v_mul_f32_e32 v34, v34, v230
	v_mul_f32_e32 v35, v35, v230
	v_mul_f32_e32 v36, v36, v230
	v_mul_f32_e32 v37, v37, v230
	v_mul_f32_e32 v38, v38, v230
	v_mul_f32_e32 v39, v39, v230
	v_mul_f32_e32 v40, v40, v230
	v_mul_f32_e32 v41, v41, v230
	v_mul_f32_e32 v42, v42, v230
	v_mul_f32_e32 v43, v43, v230
	v_mul_f32_e32 v44, v44, v230
	v_mul_f32_e32 v45, v45, v230
	v_mul_f32_e32 v46, v46, v230
	v_mul_f32_e32 v47, v47, v230
	v_mul_f32_e32 v48, v48, v230
	v_mul_f32_e32 v49, v49, v230
	v_mul_f32_e32 v50, v50, v230
	v_mul_f32_e32 v51, v51, v230
	v_mul_f32_e32 v52, v52, v230
	v_mul_f32_e32 v53, v53, v230
	v_mul_f32_e32 v54, v54, v230
	v_mul_f32_e32 v55, v55, v230
	v_mul_f32_e32 v56, v56, v230
	v_mul_f32_e32 v57, v57, v230
	v_mul_f32_e32 v58, v58, v230
	v_mul_f32_e32 v59, v59, v230
	v_mul_f32_e32 v60, v60, v230
	v_mul_f32_e32 v61, v61, v230
	v_mul_f32_e32 v62, v62, v230
	v_mul_f32_e32 v63, v63, v230
	v_sub_f32_e32 v179, v179, v221
	v_sub_f32_e32 v180, v180, v221
	v_sub_f32_e32 v181, v181, v221
	v_sub_f32_e32 v182, v182, v221
	v_sub_f32_e32 v183, v183, v221
	v_sub_f32_e32 v184, v184, v221
	v_sub_f32_e32 v185, v185, v221
	v_sub_f32_e32 v186, v186, v221
	s_branch .Lna_cont_C_b1
